# latent attention tile loop: waves 4-7 run a copy with the workgroup barrier moved between softmax and PV (V stores/loads behind it) so the two teams per SIMD alternate VALU and MFMA phases
# speedup vs baseline: 1.0711x; 1.0005x over previous
.LBB0_751:
	s_andn2_b64 vcc, exec, s[36:37]
	s_cbranch_vccnz .LBB0_774
	v_mov_b32_e32 v56, v189
	v_readlane_b32 s36, v251, 47
	v_and_b32_e32 v0, 63, v56
	v_lshlrev_b32_e32 v0, 2, v0
	v_readlane_b32 s37, v251, 48
	s_nop 4
	global_load_dword v16, v0, s[36:37]
	global_load_dword v17, v0, s[36:37] offset:256
	global_load_dword v18, v0, s[36:37] offset:512
	global_load_dword v19, v0, s[36:37] offset:768
	s_add_i32 s20, s19, 0xffffff00
	s_lshr_b32 s38, s20, 6
	s_lshl_b32 s20, s19, 6
	s_lshl_b32 s23, s38, 10
	s_and_b32 s20, s20, 0x3c0
	s_or_b32 s20, s23, s20
	v_ashrrev_i32_e32 v0, 2, v56
	s_addk_i32 s20, 0x1000
	v_and_b32_e32 v206, -16, v0
	v_and_b32_e32 v204, 15, v56
	v_add_u32_e32 v0, s20, v206
	s_lshl_b32 s21, s19, 3
	v_or_b32_e32 v2, v0, v204
	v_mov_b64_e32 v[0:1], s[6:7]
	s_and_b32 s21, s21, 0x180
	v_mad_i64_i32 v[0:1], s[36:37], v2, s0, v[0:1]
	s_lshl_b32 s36, s21, 1
	s_mov_b32 s37, s71
	v_lshl_add_u64 v[0:1], v[0:1], 0, s[36:37]
	v_and_b32_e32 v160, 48, v56
	v_lshl_add_u64 v[4:5], v[0:1], 0, v[160:161]
	s_movk_i32 s22, 0x1000
	v_add_co_u32_e32 v0, vcc, s22, v4
	v_mbcnt_hi_u32_b32 v151, -1, v194
	s_nop 0
	v_addc_co_u32_e32 v1, vcc, 0, v5, vcc
	global_load_dwordx4 v[0:3], v[0:1], off offset:1024
	v_and_b32_e32 v8, 64, v151
	s_mov_b64 s[36:37], 0x1400
	v_xor_b32_e32 v9, 32, v151
	v_add_u32_e32 v208, 64, v8
	v_lshl_add_u64 v[12:13], v[4:5], 0, s[36:37]
	v_xor_b32_e32 v10, 16, v151
	v_cmp_lt_i32_e32 vcc, v9, v208
	global_load_dwordx4 v[4:7], v[12:13], off offset:64
	v_xor_b32_e32 v11, 8, v151
	v_cndmask_b32_e32 v8, v151, v9, vcc
	v_cmp_lt_i32_e32 vcc, v10, v208
	v_lshlrev_b32_e32 v141, 2, v8
	v_xor_b32_e32 v14, 4, v151
	v_cndmask_b32_e32 v9, v151, v10, vcc
	v_cmp_lt_i32_e32 vcc, v11, v208
	v_lshlrev_b32_e32 v205, 2, v9
	s_mov_b32 s40, 0x3e000000
	v_cndmask_b32_e32 v10, v151, v11, vcc
	v_lshlrev_b32_e32 v22, 2, v10
	global_load_dwordx4 v[8:11], v[12:13], off offset:128
	v_cmp_lt_i32_e32 vcc, v14, v208
	v_xor_b32_e32 v15, 2, v151
	s_lshl_b32 s36, s38, 19
	v_cndmask_b32_e32 v14, v151, v14, vcc
	v_lshlrev_b32_e32 v25, 2, v14
	v_cmp_lt_i32_e32 vcc, v15, v208
	v_readlane_b32 s37, v251, 42
	v_ashrrev_i32_e32 v138, 4, v56
	v_cndmask_b32_e32 v15, v151, v15, vcc
	v_lshlrev_b32_e32 v26, 2, v15
	global_load_dwordx4 v[12:15], v[12:13], off offset:192
	s_or_b32 s36, s36, s37
	v_ashrrev_i32_e32 v139, 31, v138
	s_or_b32 s70, s36, s21
	v_lshlrev_b64 v[42:43], 9, v[138:139]
	v_lshlrev_b32_e32 v140, 3, v204
	v_readlane_b32 s36, v252, 55
	v_readlane_b32 s38, v252, 57
	v_readlane_b32 s37, v252, 56
	v_readlane_b32 s39, v252, 58
	v_or_b32_e32 v44, s70, v140
	v_mov_b32_e32 v45, v161
	s_barrier
	v_lshlrev_b32_e32 v207, 3, v56
	s_mov_b32 s22, 0
	v_mov_b32_e32 v154, 0xf149f2ca
	s_waitcnt vmcnt(0)
	v_mul_f32_e32 v20, v16, v17
	ds_bpermute_b32 v23, v141, v20
	s_waitcnt vmcnt(4)
	v_mul_f32_e32 v21, v18, v19
	ds_bpermute_b32 v24, v141, v21
	v_mov_b32_e32 v112, 0xf149f2ca
	s_mov_b64 s[42:43], 0x1800
	s_waitcnt lgkmcnt(1)
	v_fmac_f32_e32 v23, v16, v17
	ds_bpermute_b32 v27, v205, v23
	s_waitcnt lgkmcnt(1)
	v_fmac_f32_e32 v24, v18, v19
	ds_bpermute_b32 v28, v205, v24
	s_mov_b64 s[44:45], 0x1c00
	s_mov_b64 s[46:47], 0xf7c0000
	s_waitcnt lgkmcnt(1)
	v_add_f32_e32 v23, v23, v27
	ds_bpermute_b32 v27, v22, v23
	s_waitcnt lgkmcnt(1)
	v_add_f32_e32 v24, v24, v28
	ds_bpermute_b32 v22, v22, v24
	s_mov_b64 s[48:49], 0xfbc0000
	s_waitcnt lgkmcnt(0)
	v_add_f32_e32 v22, v24, v22
	ds_bpermute_b32 v24, v25, v22
	s_waitcnt lgkmcnt(0)
	v_add_f32_e32 v212, v22, v24
	ds_bpermute_b32 v213, v26, v212
	s_waitcnt vmcnt(3)
	v_and_b32_e32 v17, 0xffff0000, v0
	v_lshlrev_b32_e32 v16, 16, v0
	v_and_b32_e32 v19, 0xffff0000, v1
	v_lshlrev_b32_e32 v18, 16, v1
	v_and_b32_e32 v1, 0xffff0000, v2
	v_lshlrev_b32_e32 v0, 16, v2
	v_and_b32_e32 v21, 0xffff0000, v3
	v_lshlrev_b32_e32 v20, 16, v3
	v_pk_mul_f32 v[2:3], v[16:17], s[40:41] op_sel_hi:[1,0]
	v_pk_mul_f32 v[0:1], v[0:1], s[40:41] op_sel_hi:[1,0]
	v_bfe_u32 v33, v2, 16, 1
	v_add3_u32 v57, v2, v33, s94
	v_add_f32_e32 v2, v23, v27
	ds_bpermute_b32 v23, v25, v2
	v_cvt_pk_bf16_f32 v62, v0, v1
	s_waitcnt vmcnt(2)
	v_and_b32_e32 v1, 0xffff0000, v4
	v_lshlrev_b32_e32 v0, 16, v4
	v_pk_mul_f32 v[0:1], v[0:1], s[40:41] op_sel_hi:[1,0]
	v_pk_mul_f32 v[16:17], v[18:19], s[40:41] op_sel_hi:[1,0]
	s_waitcnt lgkmcnt(0)
	v_add_f32_e32 v210, v2, v23
	v_cvt_pk_bf16_f32 v74, v0, v1
	s_waitcnt vmcnt(1)
	v_and_b32_e32 v1, 0xffff0000, v8
	v_lshlrev_b32_e32 v0, 16, v8
	v_bfe_u32 v28, v3, 16, 1
	v_cvt_pk_bf16_f32 v60, v16, v17
	v_and_b32_e32 v17, 0xffff0000, v7
	v_lshlrev_b32_e32 v16, 16, v7
	v_pk_mul_f32 v[40:41], v[0:1], s[40:41] op_sel_hi:[1,0]
	v_and_b32_e32 v1, 0xffff0000, v9
	v_lshlrev_b32_e32 v0, 16, v9
	v_and_b32_e32 v37, 0xffff0000, v10
	v_lshlrev_b32_e32 v36, 16, v10
	v_add_u32_e32 v10, 0x100, v56
	v_pk_mul_f32 v[18:19], v[20:21], s[40:41] op_sel_hi:[1,0]
	v_add3_u32 v58, v3, v28, s94
	v_and_b32_e32 v3, 0xffff0000, v5
	v_lshlrev_b32_e32 v2, 16, v5
	v_and_b32_e32 v5, 0xffff0000, v6
	v_lshlrev_b32_e32 v4, 16, v6
	v_pk_mul_f32 v[6:7], v[16:17], s[40:41] op_sel_hi:[1,0]
	v_pk_mul_f32 v[8:9], v[0:1], s[40:41] op_sel_hi:[1,0]
	v_lshl_add_u64 v[0:1], v[42:43], 0, s[70:71]
	v_ashrrev_i32_e32 v136, 4, v10
	v_pk_mul_f32 v[2:3], v[2:3], s[40:41] op_sel_hi:[1,0]
	v_pk_mul_f32 v[4:5], v[4:5], s[40:41] op_sel_hi:[1,0]
	v_or_b32_e32 v0, v0, v140
	v_ashrrev_i32_e32 v137, 31, v136
	v_add_u32_e32 v10, 0x200, v56
	v_cvt_pk_bf16_f32 v72, v18, v19
	v_cvt_pk_bf16_f32 v80, v6, v7
	v_lshlrev_b64 v[0:1], 1, v[0:1]
	v_lshlrev_b64 v[16:17], 9, v[136:137]
	v_ashrrev_i32_e32 v134, 4, v10
	v_add_u32_e32 v10, 0x300, v56
	v_cvt_pk_bf16_f32 v76, v2, v3
	v_cvt_pk_bf16_f32 v78, v4, v5
	v_lshl_add_u64 v[2:3], s[36:37], 0, v[0:1]
	v_lshl_add_u64 v[4:5], s[38:39], 0, v[0:1]
	v_lshl_add_u64 v[16:17], v[16:17], 0, v[44:45]
	v_ashrrev_i32_e32 v135, 31, v134
	v_ashrrev_i32_e32 v132, 4, v10
	global_load_dwordx4 v[0:3], v[2:3], off
	s_nop 0
	global_load_dwordx4 v[4:7], v[4:5], off
	v_lshlrev_b64 v[46:47], 1, v[16:17]
	v_lshlrev_b64 v[24:25], 9, v[134:135]
	v_ashrrev_i32_e32 v133, 31, v132
	v_lshl_add_u64 v[16:17], s[36:37], 0, v[46:47]
	v_lshl_add_u64 v[20:21], s[38:39], 0, v[46:47]
	v_lshl_add_u64 v[24:25], v[24:25], 0, v[44:45]
	v_lshlrev_b64 v[32:33], 9, v[132:133]
	global_load_dwordx4 v[16:19], v[16:17], off
	s_nop 0
	global_load_dwordx4 v[20:23], v[20:21], off
	v_lshlrev_b64 v[48:49], 1, v[24:25]
	v_lshl_add_u64 v[32:33], v[32:33], 0, v[44:45]
	v_lshl_add_u64 v[24:25], s[36:37], 0, v[48:49]
	v_lshl_add_u64 v[28:29], s[38:39], 0, v[48:49]
	v_lshlrev_b64 v[50:51], 1, v[32:33]
	ds_bpermute_b32 v211, v26, v210
	global_load_dwordx4 v[24:27], v[24:25], off
	s_nop 0
	global_load_dwordx4 v[28:31], v[28:29], off
	v_lshl_add_u64 v[32:33], s[36:37], 0, v[50:51]
	global_load_dwordx4 v[32:35], v[32:33], off
	v_pk_mul_f32 v[52:53], v[36:37], s[40:41] op_sel_hi:[1,0]
	v_lshl_add_u64 v[36:37], s[38:39], 0, v[50:51]
	global_load_dwordx4 v[36:39], v[36:37], off
	v_and_b32_e32 v55, 0xffff0000, v11
	v_lshlrev_b32_e32 v54, 16, v11
	v_pk_mul_f32 v[10:11], v[54:55], s[40:41] op_sel_hi:[1,0]
	v_bfe_u32 v54, v11, 16, 1
	v_bfe_u32 v55, v10, 16, 1
	v_add3_u32 v55, v10, v55, s94
	v_add3_u32 v54, v11, v54, s94
	s_waitcnt vmcnt(8)
	v_and_b32_e32 v11, 0xffff0000, v13
	v_lshlrev_b32_e32 v10, 16, v13
	v_pk_mul_f32 v[10:11], v[10:11], s[40:41] op_sel_hi:[1,0]
	v_cvt_pk_bf16_f32 v82, v40, v41
	v_cvt_pk_bf16_f32 v84, v8, v9
	v_and_b32_e32 v9, 0xffff0000, v12
	v_lshlrev_b32_e32 v8, 16, v12
	v_and_b32_e32 v13, 0xffff0000, v14
	v_lshlrev_b32_e32 v12, 16, v14
	v_and_b32_e32 v41, 0xffff0000, v15
	v_lshlrev_b32_e32 v40, 16, v15
	v_bfe_u32 v67, v10, 16, 1
	v_pk_mul_f32 v[8:9], v[8:9], s[40:41] op_sel_hi:[1,0]
	v_pk_mul_f32 v[12:13], v[12:13], s[40:41] op_sel_hi:[1,0]
	v_pk_mul_f32 v[14:15], v[40:41], s[40:41] op_sel_hi:[1,0]
	v_add3_u32 v87, v10, v67, s94
	s_movk_i32 s40, 0x110
	v_lshlrev_b32_e32 v10, 4, v56
	v_mul_lo_u32 v214, v138, s40
	v_and_b32_e32 v215, 0xf0, v10
	s_movk_i32 s41, 0x120
	v_add3_u32 v10, s17, v214, v215
	v_mul_lo_u32 v216, v138, s41
	v_mul_lo_u32 v217, v136, s40
	v_mul_lo_u32 v218, v136, s41
	v_mul_lo_u32 v219, v134, s40
	v_mul_lo_u32 v220, v134, s41
	v_mul_lo_u32 v221, v132, s40
	v_mul_lo_u32 v222, v132, s41
	s_mov_b64 s[40:41], 0x10000
	v_cvt_pk_bf16_f32 v14, v14, v15
	v_cvt_pk_bf16_f32 v52, v52, v53
	v_bfe_u32 v66, v11, 16, 1
	v_cvt_pk_bf16_f32 v86, v8, v9
	s_waitcnt vmcnt(7)
	ds_write_b128 v10, v[0:3]
	v_add3_u32 v0, s17, v216, v215
	s_waitcnt vmcnt(6)
	ds_write_b128 v0, v[4:7] offset:17408
	v_add3_u32 v0, s17, v217, v215
	v_add3_u32 v88, v11, v66, s94
	v_cvt_pk_bf16_f32 v12, v12, v13
	v_lshrrev_b32_e32 v9, 2, v56
	s_waitcnt vmcnt(5)
	ds_write_b128 v0, v[16:19]
	v_add3_u32 v0, s17, v218, v215
	s_waitcnt vmcnt(4)
	ds_write_b128 v0, v[20:23] offset:17408
	v_add3_u32 v0, s17, v219, v215
	v_bfe_u32 v8, v56, 2, 2
	v_and_b32_e32 v209, 12, v9
	v_or_b32_e32 v8, v209, v8
	s_waitcnt vmcnt(3)
	ds_write_b128 v0, v[24:27]
	v_add3_u32 v0, s17, v220, v215
	s_waitcnt vmcnt(2)
	ds_write_b128 v0, v[28:31] offset:17408
	v_add3_u32 v0, s17, v221, v215
	s_waitcnt vmcnt(1)
	ds_write_b128 v0, v[32:35]
	v_add3_u32 v0, s17, v222, v215
	s_waitcnt vmcnt(0)
	ds_write_b128 v0, v[36:39] offset:17408
	v_lshl_add_u64 v[0:1], v[42:43], 0, v[44:45]
	v_lshl_add_u64 v[0:1], v[0:1], 1, v[166:167]
	v_lshl_add_u64 v[2:3], s[36:37], 0, v[0:1]
	v_lshl_add_u64 v[0:1], s[38:39], 0, v[0:1]
	global_load_dwordx4 v[16:19], v[2:3], off
	global_load_dwordx4 v[20:23], v[0:1], off
	v_lshl_add_u64 v[0:1], v[46:47], 0, s[40:41]
	v_lshl_add_u64 v[2:3], s[36:37], 0, v[0:1]
	v_lshl_add_u64 v[0:1], s[38:39], 0, v[0:1]
	global_load_dwordx4 v[24:27], v[2:3], off
	global_load_dwordx4 v[28:31], v[0:1], off
	v_lshl_add_u64 v[0:1], v[48:49], 0, s[40:41]
	v_lshl_add_u64 v[2:3], s[36:37], 0, v[0:1]
	v_lshl_add_u64 v[0:1], s[38:39], 0, v[0:1]
	global_load_dwordx4 v[36:39], v[2:3], off
	global_load_dwordx4 v[40:43], v[0:1], off
	v_lshl_add_u64 v[0:1], v[50:51], 0, s[40:41]
	v_lshl_add_u64 v[2:3], s[36:37], 0, v[0:1]
	v_lshl_add_u64 v[0:1], s[38:39], 0, v[0:1]
	global_load_dwordx4 v[64:67], v[2:3], off
	global_load_dwordx4 v[68:71], v[0:1], off
	v_mul_u32_u24_e32 v32, 0x110, v204
	v_add3_u32 v224, s17, v160, v32
	v_lshlrev_b64 v[32:33], 10, v[132:133]
	v_lshlrev_b32_e32 v160, 1, v44
	v_lshl_add_u64 v[32:33], v[32:33], 0, v[160:161]
	v_lshl_add_u64 v[144:145], s[30:31], 0, v[32:33]
	v_add_u32_e32 v32, s23, v132
	v_add_u32_e32 v133, 0xe80, v32
	v_lshlrev_b64 v[32:33], 10, v[134:135]
	v_lshl_add_u64 v[32:33], v[32:33], 0, v[160:161]
	v_lshl_add_u64 v[146:147], s[30:31], 0, v[32:33]
	v_add_u32_e32 v32, s23, v134
	v_add_u32_e32 v135, 0xe80, v32
	v_lshlrev_b64 v[32:33], 10, v[136:137]
	v_lshl_add_u64 v[32:33], v[32:33], 0, v[160:161]
	v_lshl_add_u64 v[148:149], s[30:31], 0, v[32:33]
	v_add_u32_e32 v32, s23, v136
	v_add_u32_e32 v137, 0xe80, v32
	v_lshlrev_b64 v[32:33], 10, v[138:139]
	v_lshl_add_u64 v[32:33], v[32:33], 0, v[160:161]
	v_lshl_add_u64 v[152:153], s[30:31], 0, v[32:33]
	v_add_u32_e32 v32, s23, v138
	v_mul_u32_u24_e32 v8, 0x120, v8
	v_and_b32_e32 v9, 24, v207
	v_readlane_b32 s36, v251, 56
	v_add_u32_e32 v139, 0xe80, v32
	v_mov_b32_e32 v32, 0
	v_add3_u32 v223, v9, s36, v8
	v_mov_b32_e32 v3, v72
	v_mov_b32_e32 v2, v62
	v_mov_b32_e32 v1, v60
	v_perm_b32 v0, v58, v57, s95
	v_mov_b32_e32 v7, v80
	v_mov_b32_e32 v6, v78
	v_mov_b32_e32 v5, v76
	v_mov_b32_e32 v4, v74
	v_perm_b32 v11, v54, v55, s95
	v_mov_b32_e32 v10, v52
	v_mov_b32_e32 v9, v84
	v_mov_b32_e32 v8, v82
	v_mov_b32_e32 v15, v14
	v_mov_b32_e32 v14, v12
	v_perm_b32 v13, v88, v87, s95
	v_mov_b32_e32 v12, v86
	s_mov_b64 s[38:39], 0
	v_mov_b32_e32 v33, v32
	v_mov_b32_e32 v34, v32
	v_mov_b32_e32 v35, v32
	v_mov_b32_e32 v44, v32
	v_mov_b32_e32 v45, v32
	v_mov_b32_e32 v46, v32
	v_mov_b32_e32 v47, v32
	v_mov_b32_e32 v60, v32
	v_mov_b32_e32 v61, v32
	v_mov_b32_e32 v62, v32
	v_mov_b32_e32 v63, v32
	v_mov_b32_e32 v76, v32
	v_mov_b32_e32 v77, v32
	v_mov_b32_e32 v78, v32
	v_mov_b32_e32 v79, v32
	v_mov_b32_e32 v80, v32
	v_mov_b32_e32 v81, v32
	v_mov_b32_e32 v82, v32
	v_mov_b32_e32 v83, v32
	v_mov_b32_e32 v84, v32
	v_mov_b32_e32 v85, v32
	v_mov_b32_e32 v86, v32
	v_mov_b32_e32 v87, v32
	v_mov_b32_e32 v88, v32
	v_mov_b32_e32 v89, v32
	v_mov_b32_e32 v90, v32
	v_mov_b32_e32 v91, v32
	v_mov_b32_e32 v96, v32
	v_mov_b32_e32 v97, v32
	v_mov_b32_e32 v98, v32
	v_mov_b32_e32 v99, v32
	v_mov_b32_e32 v92, v32
	v_mov_b32_e32 v93, v32
	v_mov_b32_e32 v94, v32
	v_mov_b32_e32 v95, v32
	v_mov_b32_e32 v100, v32
	v_mov_b32_e32 v101, v32
	v_mov_b32_e32 v102, v32
	v_mov_b32_e32 v103, v32
	v_mov_b32_e32 v104, v32
	v_mov_b32_e32 v105, v32
	v_mov_b32_e32 v106, v32
	v_mov_b32_e32 v107, v32
	v_mov_b32_e32 v108, v32
	v_mov_b32_e32 v109, v32
	v_mov_b32_e32 v110, v32
	v_mov_b32_e32 v111, v32
	v_mov_b32_e32 v72, v32
	v_mov_b32_e32 v73, v32
	v_mov_b32_e32 v74, v32
	v_mov_b32_e32 v75, v32
	v_mov_b32_e32 v56, v32
	v_mov_b32_e32 v57, v32
	v_mov_b32_e32 v58, v32
	v_mov_b32_e32 v59, v32
	v_mov_b32_e32 v52, v32
	v_mov_b32_e32 v53, v32
	v_mov_b32_e32 v54, v32
	v_mov_b32_e32 v55, v32
	v_mov_b32_e32 v48, v32
	v_mov_b32_e32 v49, v32
	v_mov_b32_e32 v50, v32
	v_mov_b32_e32 v51, v32
	v_mov_b32_e32 v142, v32
	v_mov_b32_e32 v143, v32
	s_waitcnt lgkmcnt(0)
	s_barrier
	v_readlane_b32 s100, v251, 53
	s_nop 3
	s_cmp_eq_u32 s100, 1
	s_cbranch_scc1 .Lal1_entry
	s_branch .LBB0_755

.Lal1_entry:
	v_mov_b32_e32 v255, 0
.Lal1_head:
	s_and_b32 s23, s22, 1
	s_cmp_gt_u32 s22, 22
	s_cbranch_scc1 .Lal1_body
	s_xor_b32 s36, s23, 1
	s_mul_i32 s36, s36, 0x8c00
	s_add_i32 s36, s17, s36
	v_add3_u32 v113, s36, v214, v215
	s_waitcnt vmcnt(7)
	ds_write_b128 v113, v[16:19]
	v_add3_u32 v113, s36, v217, v215
	s_waitcnt vmcnt(5)
	ds_write_b128 v113, v[24:27]
	v_add3_u32 v113, s36, v219, v215
	s_waitcnt vmcnt(3)
	ds_write_b128 v113, v[36:39]
	v_add3_u32 v113, s36, v221, v215
	s_waitcnt vmcnt(1)
	ds_write_b128 v113, v[64:67]
	s_cmp_eq_u32 s38, 0x160000
	s_cbranch_scc1 .Lal1_body
	s_cmp_gt_u32 s22, 5
	s_cbranch_scc0 .Lal1_kc
	v_lshlrev_b32_e32 v160, 1, v140
	s_lshl_b32 s70, s21, 1
	v_mov_b64_e32 v[16:17], s[6:7]
	v_mad_i64_i32 v[16:17], s[100:101], v139, s0, v[16:17]
	v_lshl_add_u64 v[16:17], v[16:17], 0, s[70:71]
	v_lshl_add_u64 v[16:17], v[16:17], 0, v[160:161]
	v_lshl_add_u64 v[16:17], v[16:17], 0, s[42:43]
	v_mov_b64_e32 v[24:25], s[6:7]
	v_mad_i64_i32 v[24:25], s[100:101], v137, s0, v[24:25]
	v_lshl_add_u64 v[24:25], v[24:25], 0, s[70:71]
	v_lshl_add_u64 v[24:25], v[24:25], 0, v[160:161]
	v_lshl_add_u64 v[24:25], v[24:25], 0, s[42:43]
	v_mov_b64_e32 v[36:37], s[6:7]
	v_mad_i64_i32 v[36:37], s[100:101], v135, s0, v[36:37]
	v_lshl_add_u64 v[36:37], v[36:37], 0, s[70:71]
	v_lshl_add_u64 v[36:37], v[36:37], 0, v[160:161]
	v_lshl_add_u64 v[36:37], v[36:37], 0, s[42:43]
	v_mov_b64_e32 v[64:65], s[6:7]
	v_mad_i64_i32 v[64:65], s[100:101], v133, s0, v[64:65]
	v_lshl_add_u64 v[64:65], v[64:65], 0, s[70:71]
	v_lshl_add_u64 v[64:65], v[64:65], 0, v[160:161]
	v_lshl_add_u64 v[64:65], v[64:65], 0, s[42:43]
	s_branch .Lal1_kld
.Lal1_kc:
	v_lshl_add_u64 v[16:17], v[152:153], 0, s[38:39]
	v_lshl_add_u64 v[16:17], v[16:17], 0, s[46:47]
	v_lshl_add_u64 v[24:25], v[148:149], 0, s[38:39]
	v_lshl_add_u64 v[24:25], v[24:25], 0, s[46:47]
	v_lshl_add_u64 v[36:37], v[146:147], 0, s[38:39]
	v_lshl_add_u64 v[36:37], v[36:37], 0, s[46:47]
	v_lshl_add_u64 v[64:65], v[144:145], 0, s[38:39]
	v_lshl_add_u64 v[64:65], v[64:65], 0, s[46:47]
.Lal1_kld:
	global_load_dwordx4 v[16:19], v[16:17], off
	global_load_dwordx4 v[24:27], v[24:25], off
	global_load_dwordx4 v[36:39], v[36:37], off
	global_load_dwordx4 v[64:67], v[64:65], off
.Lal1_body:
	s_mul_i32 s23, s23, 0x8c00
	v_add_u32_e32 v225, s23, v223
	v_add_u32_e32 v113, s23, v224
	ds_read_b128 v[114:117], v113
	ds_read_b128 v[118:121], v113 offset:64
	s_waitcnt lgkmcnt(1)
	v_mfma_f32_16x16x32_bf16 v[114:117], v[114:117], v[0:3], 0
	s_waitcnt lgkmcnt(0)
	v_mfma_f32_16x16x32_bf16 v[156:159], v[118:121], v[4:7], v[114:117]
	ds_read_b128 v[118:121], v113 offset:4416
	s_nop 4
	ds_read_b128 v[114:117], v113 offset:4352
	s_waitcnt lgkmcnt(0)
	v_mfma_f32_16x16x32_bf16 v[114:117], v[114:117], v[0:3], 0
	v_mfma_f32_16x16x32_bf16 v[172:175], v[118:121], v[4:7], v[114:117]
	s_nop 6
	ds_read_b128 v[114:117], v113 offset:8704
	ds_read_b128 v[118:121], v113 offset:8768
	s_waitcnt lgkmcnt(1)
	v_mfma_f32_16x16x32_bf16 v[114:117], v[114:117], v[0:3], 0
	s_waitcnt lgkmcnt(0)
	v_mfma_f32_16x16x32_bf16 v[178:181], v[118:121], v[4:7], v[114:117]
	ds_read_b128 v[118:121], v113 offset:13120
	s_nop 4
	ds_read_b128 v[114:117], v113 offset:13056
	s_waitcnt lgkmcnt(0)
	v_mfma_f32_16x16x32_bf16 v[114:117], v[114:117], v[0:3], 0
	v_mfma_f32_16x16x32_bf16 v[228:231], v[118:121], v[4:7], v[114:117]
	s_nop 6
	ds_read_b128 v[114:117], v113 offset:128
	ds_read_b128 v[118:121], v113 offset:192
	ds_read_b128 v[122:125], v113 offset:4480
	s_waitcnt lgkmcnt(2)
	v_mfma_f32_16x16x32_bf16 v[114:117], v[114:117], v[8:11], 0
	s_waitcnt lgkmcnt(1)
	v_mfma_f32_16x16x32_bf16 v[128:131], v[118:121], v[12:15], v[114:117]
	s_nop 5
	ds_read_b128 v[114:117], v113 offset:4544
	s_waitcnt lgkmcnt(1)
	v_mfma_f32_16x16x32_bf16 v[122:125], v[122:125], v[8:11], 0
	s_waitcnt lgkmcnt(0)
	v_mfma_f32_16x16x32_bf16 v[120:123], v[114:117], v[12:15], v[122:125]
	ds_read_b128 v[114:117], v113 offset:8832
	s_nop 4
	ds_read_b128 v[124:127], v113 offset:8896
	s_waitcnt lgkmcnt(1)
	v_mfma_f32_16x16x32_bf16 v[114:117], v[114:117], v[8:11], 0
	s_waitcnt lgkmcnt(0)
	v_mfma_f32_16x16x32_bf16 v[116:119], v[124:127], v[12:15], v[114:117]
	ds_read_b128 v[124:127], v113 offset:13248
	ds_read_b128 v[182:185], v113 offset:13184
	s_waitcnt lgkmcnt(0)
	v_mfma_f32_16x16x32_bf16 v[182:185], v[182:185], v[8:11], 0
	v_mfma_f32_16x16x32_bf16 v[124:127], v[124:127], v[12:15], v[182:185]
	v_max3_f32 v113, v156, s8, v157
	v_max3_f32 v113, v113, v158, v159
	v_max3_f32 v113, v113, v172, v173
	v_max3_f32 v113, v113, v174, v175
	v_max3_f32 v113, v113, v178, v179
	v_max3_f32 v113, v113, v180, v181
	v_max3_f32 v113, v113, v228, v229
	v_max3_f32 v113, v113, v230, v231
	ds_bpermute_b32 v114, v205, v113
	s_waitcnt lgkmcnt(0)
	v_max_f32_e32 v114, v114, v114
	v_max_f32_e32 v113, v113, v114
	ds_bpermute_b32 v114, v141, v113
	s_waitcnt lgkmcnt(0)
	v_max3_f32 v226, v112, v113, v114
	v_sub_f32_e32 v114, v157, v226
	v_mul_f32_e32 v114, 0x3fb8aa3b, v114
	v_exp_f32_e32 v176, v114
	v_sub_f32_e32 v114, v158, v226
	v_sub_f32_e32 v113, v156, v226
	v_mul_f32_e32 v114, 0x3fb8aa3b, v114
	v_mul_f32_e32 v113, 0x3fb8aa3b, v113
	v_exp_f32_e32 v158, v114
	v_sub_f32_e32 v114, v159, v226
	v_exp_f32_e32 v156, v113
	v_mul_f32_e32 v114, 0x3fb8aa3b, v114
	v_exp_f32_e32 v182, v114
	v_sub_f32_e32 v114, v172, v226
	v_mul_f32_e32 v114, 0x3fb8aa3b, v114
	v_exp_f32_e32 v172, v114
	v_sub_f32_e32 v114, v173, v226
	v_add_f32_e32 v113, 0, v156
	v_mul_f32_e32 v114, 0x3fb8aa3b, v114
	v_add_f32_e32 v113, v176, v113
	v_exp_f32_e32 v184, v114
	v_add_f32_e32 v113, v158, v113
	v_add_f32_e32 v113, v182, v113
	v_add_f32_e32 v113, v172, v113
	v_add_f32_e32 v187, v184, v113
	v_sub_f32_e32 v113, v174, v226
	v_mul_f32_e32 v113, 0x3fb8aa3b, v113
	v_exp_f32_e32 v177, v113
	v_sub_f32_e32 v113, v175, v226
	v_mul_f32_e32 v113, 0x3fb8aa3b, v113
	v_exp_f32_e32 v183, v113
	v_sub_f32_e32 v113, v178, v226
	v_mul_f32_e32 v113, 0x3fb8aa3b, v113
	v_exp_f32_e32 v155, v113
	v_sub_f32_e32 v113, v179, v226
	v_mul_f32_e32 v113, 0x3fb8aa3b, v113
	v_exp_f32_e32 v159, v113
	v_sub_f32_e32 v113, v180, v226
	v_mul_f32_e32 v113, 0x3fb8aa3b, v113
	v_exp_f32_e32 v157, v113
	v_sub_f32_e32 v113, v181, v226
	v_mul_f32_e32 v113, 0x3fb8aa3b, v113
	v_exp_f32_e32 v175, v113
	v_sub_f32_e32 v113, v228, v226
	v_mul_f32_e32 v113, 0x3fb8aa3b, v113
	v_exp_f32_e32 v173, v113
	v_sub_f32_e32 v113, v229, v226
	v_mul_f32_e32 v113, 0x3fb8aa3b, v113
	v_exp_f32_e32 v181, v113
	v_sub_f32_e32 v113, v230, v226
	v_sub_f32_e32 v112, v112, v226
	v_mul_f32_e32 v113, 0x3fb8aa3b, v113
	v_mul_f32_e32 v112, 0x3fb8aa3b, v112
	v_exp_f32_e32 v179, v113
	v_sub_f32_e32 v113, v231, v226
	v_mul_f32_e32 v113, 0x3fb8aa3b, v113
	v_exp_f32_e32 v160, v112
	v_exp_f32_e32 v185, v113
	v_pk_mul_f32 v[112:113], v[108:109], v[160:161] op_sel_hi:[1,0]
	v_pk_mul_f32 v[108:109], v[104:105], v[160:161] op_sel_hi:[1,0]
	v_pk_mul_f32 v[104:105], v[100:101], v[160:161] op_sel_hi:[1,0]
	v_pk_mul_f32 v[100:101], v[92:93], v[160:161] op_sel_hi:[1,0]
	v_pk_mul_f32 v[92:93], v[96:97], v[160:161] op_sel_hi:[1,0]
	v_max3_f32 v96, v128, s8, v129
	v_max3_f32 v96, v96, v130, v131
	v_max3_f32 v96, v96, v120, v121
	v_max3_f32 v96, v96, v122, v123
	v_max3_f32 v96, v96, v116, v117
	v_max3_f32 v96, v96, v118, v119
	v_max3_f32 v96, v96, v124, v125
	v_cvt_pk_bf16_f32 v242, v177, v183
	v_max3_f32 v96, v96, v126, v127
	v_cvt_pk_bf16_f32 v234, v179, v185
	ds_bpermute_b32 v97, v205, v96
	v_pk_mul_f32 v[114:115], v[110:111], v[160:161] op_sel_hi:[1,0]
	v_pk_mul_f32 v[110:111], v[106:107], v[160:161] op_sel_hi:[1,0]
	v_pk_mul_f32 v[106:107], v[102:103], v[160:161] op_sel_hi:[1,0]
	v_pk_mul_f32 v[102:103], v[94:95], v[160:161] op_sel_hi:[1,0]
	s_waitcnt lgkmcnt(0)
	v_max_f32_e32 v97, v97, v97
	v_max_f32_e32 v96, v96, v97
	ds_bpermute_b32 v97, v141, v96
	v_pk_mul_f32 v[94:95], v[98:99], v[160:161] op_sel_hi:[1,0]
	s_waitcnt lgkmcnt(0)
	v_max3_f32 v227, v154, v96, v97
	v_sub_f32_e32 v98, v129, v227
	v_mul_f32_e32 v98, 0x3fb8aa3b, v98
	v_exp_f32_e32 v129, v98
	v_sub_f32_e32 v98, v130, v227
	v_sub_f32_e32 v97, v128, v227
	v_mul_f32_e32 v98, 0x3fb8aa3b, v98
	v_mul_f32_e32 v97, 0x3fb8aa3b, v97
	v_exp_f32_e32 v130, v98
	v_sub_f32_e32 v98, v131, v227
	v_exp_f32_e32 v128, v97
	v_mul_f32_e32 v98, 0x3fb8aa3b, v98
	v_exp_f32_e32 v131, v98
	v_sub_f32_e32 v98, v120, v227
	v_mul_f32_e32 v98, 0x3fb8aa3b, v98
	v_exp_f32_e32 v244, v98
	v_sub_f32_e32 v98, v121, v227
	v_add_f32_e32 v97, 0, v128
	v_mul_f32_e32 v98, 0x3fb8aa3b, v98
	v_add_f32_e32 v97, v129, v97
	v_exp_f32_e32 v245, v98
	v_add_f32_e32 v97, v130, v97
	v_add_f32_e32 v97, v131, v97
	v_add_f32_e32 v97, v244, v97
	v_add_f32_e32 v186, v245, v97
	v_sub_f32_e32 v97, v122, v227
	v_mul_f32_e32 v97, 0x3fb8aa3b, v97
	v_cvt_pk_bf16_f32 v237, v156, v176
	v_exp_f32_e32 v176, v97
	v_sub_f32_e32 v97, v123, v227
	v_bfe_u32 v174, v182, 16, 1
	v_mul_f32_e32 v97, 0x3fb8aa3b, v97
	v_add3_u32 v239, v182, v174, s94
	v_exp_f32_e32 v182, v97
	v_sub_f32_e32 v97, v116, v227
	v_mul_f32_e32 v97, 0x3fb8aa3b, v97
	v_bfe_u32 v178, v158, 16, 1
	v_sub_f32_e32 v96, v154, v227
	v_exp_f32_e32 v154, v97
	v_sub_f32_e32 v97, v117, v227
	v_add3_u32 v238, v158, v178, s94
	v_mul_f32_e32 v97, 0x3fb8aa3b, v97
	v_exp_f32_e32 v158, v97
	v_sub_f32_e32 v97, v118, v227
	v_mul_f32_e32 v97, 0x3fb8aa3b, v97
	v_cvt_pk_bf16_f32 v231, v157, v175
	v_exp_f32_e32 v156, v97
	v_sub_f32_e32 v97, v119, v227
	v_mul_f32_e32 v97, 0x3fb8aa3b, v97
	v_exp_f32_e32 v174, v97
	v_sub_f32_e32 v97, v124, v227
	v_cvt_pk_bf16_f32 v240, v172, v184
	v_mul_f32_e32 v97, 0x3fb8aa3b, v97
	v_cvt_pk_bf16_f32 v229, v155, v159
	v_exp_f32_e32 v172, v97
	v_sub_f32_e32 v97, v125, v227
	v_mul_f32_e32 v97, 0x3fb8aa3b, v97
	v_exp_f32_e32 v180, v97
	v_sub_f32_e32 v97, v126, v227
	v_mul_f32_e32 v97, 0x3fb8aa3b, v97
	v_exp_f32_e32 v178, v97
	v_sub_f32_e32 v97, v127, v227
	v_mul_f32_e32 v96, 0x3fb8aa3b, v96
	v_mul_f32_e32 v97, 0x3fb8aa3b, v97
	v_exp_f32_e32 v184, v97
	v_exp_f32_e32 v120, v96
	v_pk_add_f32 v[96:97], v[176:177], v[186:187]
	v_pk_add_f32 v[96:97], v[182:183], v[96:97]
	v_mov_b32_e32 v121, v160
	v_pk_add_f32 v[96:97], v[154:155], v[96:97]
	v_cvt_pk_bf16_f32 v232, v173, v181
	v_pk_add_f32 v[96:97], v[158:159], v[96:97]
	v_pk_mul_f32 v[98:99], v[62:63], v[120:121] op_sel_hi:[1,0]
	v_pk_add_f32 v[96:97], v[156:157], v[96:97]
	v_pk_mul_f32 v[62:63], v[34:35], v[120:121] op_sel_hi:[1,0]
	v_pk_add_f32 v[96:97], v[174:175], v[96:97]
	v_pk_mul_f32 v[34:35], v[74:75], v[120:121] op_sel_hi:[1,0]
	v_pk_add_f32 v[96:97], v[172:173], v[96:97]
	v_pk_add_f32 v[96:97], v[180:181], v[96:97]
	v_pk_add_f32 v[96:97], v[178:179], v[96:97]
	v_pk_mul_f32 v[90:91], v[90:91], v[160:161] op_sel_hi:[1,0]
	v_pk_add_f32 v[96:97], v[184:185], v[96:97]
	v_pk_mul_f32 v[88:89], v[88:89], v[160:161] op_sel_hi:[1,0]
	v_pk_mul_f32 v[86:87], v[86:87], v[160:161] op_sel_hi:[1,0]
	v_pk_mul_f32 v[84:85], v[84:85], v[160:161] op_sel_hi:[1,0]
	v_pk_mul_f32 v[82:83], v[82:83], v[160:161] op_sel_hi:[1,0]
	v_pk_mul_f32 v[80:81], v[80:81], v[160:161] op_sel_hi:[1,0]
	v_pk_fma_f32 v[142:143], v[142:143], v[120:121], v[96:97]
	v_pk_mul_f32 v[118:119], v[78:79], v[120:121] op_sel_hi:[1,0]
	v_pk_mul_f32 v[116:117], v[76:77], v[120:121] op_sel_hi:[1,0]
	v_pk_mul_f32 v[96:97], v[60:61], v[120:121] op_sel_hi:[1,0]
	v_pk_mul_f32 v[78:79], v[46:47], v[120:121] op_sel_hi:[1,0]
	v_pk_mul_f32 v[76:77], v[44:45], v[120:121] op_sel_hi:[1,0]
	v_pk_mul_f32 v[60:61], v[32:33], v[120:121] op_sel_hi:[1,0]
	v_pk_mul_f32 v[32:33], v[72:73], v[120:121] op_sel_hi:[1,0]
	v_pk_mul_f32 v[46:47], v[58:59], v[120:121] op_sel_hi:[1,0]
	v_pk_mul_f32 v[44:45], v[56:57], v[120:121] op_sel_hi:[1,0]
	v_cvt_pk_bf16_f32 v173, v128, v129
	v_cvt_pk_bf16_f32 v175, v130, v131
	v_cvt_pk_bf16_f32 v177, v244, v245
	v_cvt_pk_bf16_f32 v247, v154, v158
	v_cvt_pk_bf16_f32 v248, v156, v174
	v_add_u32_e32 v128, 0x1200, v225
	v_add_u32_e32 v129, 32, v225
	v_add_u32_e32 v130, 0x1220, v225
	v_add_u32_e32 v131, 64, v225
	v_add_u32_e32 v154, 0x1240, v225
	v_add_u32_e32 v156, 0x60, v225
	v_pk_mul_f32 v[54:55], v[54:55], v[120:121] op_sel_hi:[1,0]
	v_pk_mul_f32 v[52:53], v[52:53], v[120:121] op_sel_hi:[1,0]
	v_pk_mul_f32 v[50:51], v[50:51], v[120:121] op_sel_hi:[1,0]
	v_pk_mul_f32 v[48:49], v[48:49], v[120:121] op_sel_hi:[1,0]
	v_cvt_pk_bf16_f32 v249, v172, v180
	v_cvt_pk_bf16_f32 v250, v178, v184
	v_add_u32_e32 v172, 0x1260, v225
	s_waitcnt lgkmcnt(0)
	s_barrier
	s_cmp_gt_u32 s22, 22
	s_cbranch_scc1 .Lal1_pv
	s_and_b32 s100, s22, 1
	s_xor_b32 s100, s100, 1
	s_mul_i32 s100, s100, 0x8c00
	s_add_i32 s100, s17, s100
	v_add3_u32 v254, s100, v216, v215
	s_waitcnt vmcnt(3)
	ds_write_b128 v254, v[20:23] offset:17408
	v_add3_u32 v254, s100, v218, v215
	s_waitcnt vmcnt(2)
	ds_write_b128 v254, v[28:31] offset:17408
	v_add3_u32 v254, s100, v220, v215
	s_waitcnt vmcnt(1)
	ds_write_b128 v254, v[40:43] offset:17408
	v_add3_u32 v254, s100, v222, v215
	s_waitcnt vmcnt(0)
	ds_write_b128 v254, v[68:71] offset:17408
	s_cmp_eq_u32 s38, 0x160000
	s_cbranch_scc1 .Lal1_pv
	s_cmp_gt_u32 s22, 5
	s_cbranch_scc0 .Lal1_vc
	v_lshlrev_b32_e32 v254, 1, v140
	s_lshl_b32 s70, s21, 1
	v_mov_b64_e32 v[20:21], s[6:7]
	v_mad_i64_i32 v[20:21], s[100:101], v139, s0, v[20:21]
	v_lshl_add_u64 v[20:21], v[20:21], 0, s[70:71]
	v_lshl_add_u64 v[20:21], v[20:21], 0, v[254:255]
	v_lshl_add_u64 v[20:21], v[20:21], 0, s[44:45]
	v_mov_b64_e32 v[28:29], s[6:7]
	v_mad_i64_i32 v[28:29], s[100:101], v137, s0, v[28:29]
	v_lshl_add_u64 v[28:29], v[28:29], 0, s[70:71]
	v_lshl_add_u64 v[28:29], v[28:29], 0, v[254:255]
	v_lshl_add_u64 v[28:29], v[28:29], 0, s[44:45]
	v_mov_b64_e32 v[40:41], s[6:7]
	v_mad_i64_i32 v[40:41], s[100:101], v135, s0, v[40:41]
	v_lshl_add_u64 v[40:41], v[40:41], 0, s[70:71]
	v_lshl_add_u64 v[40:41], v[40:41], 0, v[254:255]
	v_lshl_add_u64 v[40:41], v[40:41], 0, s[44:45]
	v_mov_b64_e32 v[68:69], s[6:7]
	v_mad_i64_i32 v[68:69], s[100:101], v133, s0, v[68:69]
	v_lshl_add_u64 v[68:69], v[68:69], 0, s[70:71]
	v_lshl_add_u64 v[68:69], v[68:69], 0, v[254:255]
	v_lshl_add_u64 v[68:69], v[68:69], 0, s[44:45]
	s_branch .Lal1_vld
.Lal1_vc:
	v_lshl_add_u64 v[20:21], v[152:153], 0, s[38:39]
	v_lshl_add_u64 v[20:21], v[20:21], 0, s[48:49]
	v_lshl_add_u64 v[28:29], v[148:149], 0, s[38:39]
	v_lshl_add_u64 v[28:29], v[28:29], 0, s[48:49]
	v_lshl_add_u64 v[40:41], v[146:147], 0, s[38:39]
	v_lshl_add_u64 v[40:41], v[40:41], 0, s[48:49]
	v_lshl_add_u64 v[68:69], v[144:145], 0, s[38:39]
	v_lshl_add_u64 v[68:69], v[68:69], 0, s[48:49]
.Lal1_vld:
	global_load_dwordx4 v[20:23], v[20:21], off
	global_load_dwordx4 v[28:31], v[28:29], off
	global_load_dwordx4 v[40:43], v[40:41], off
	global_load_dwordx4 v[68:71], v[68:69], off
.Lal1_pv:
	ds_read_b64_tr_b16 v[124:125], v225
	ds_read_b64_tr_b16 v[126:127], v128
	ds_read_b64_tr_b16 v[120:121], v129
	ds_read_b64_tr_b16 v[122:123], v130
	ds_read_b64_tr_b16 v[72:73], v131
	ds_read_b64_tr_b16 v[74:75], v154
	ds_read_b64_tr_b16 v[56:57], v156
	ds_read_b64_tr_b16 v[58:59], v172
	s_waitcnt lgkmcnt(0)
	v_mov_b32_e32 v131, v242
	v_mov_b32_e32 v130, v240
	v_perm_b32 v129, v239, v238, s95
	v_mov_b32_e32 v128, v237
	v_mov_b32_e32 v156, v177
	v_mov_b32_e32 v155, v175
	v_mov_b32_e32 v154, v173
	v_cvt_pk_bf16_f32 v157, v176, v182
	v_mfma_f32_16x16x32_bf16 v[112:115], v[124:127], v[128:131], v[112:115]
	s_nop 0
	v_mfma_f32_16x16x32_bf16 v[116:119], v[124:127], v[154:157], v[116:119]
	v_mfma_f32_16x16x32_bf16 v[124:127], v[120:123], v[128:131], v[108:111]
	v_mfma_f32_16x16x32_bf16 v[96:99], v[120:123], v[154:157], v[96:99]
	v_mfma_f32_16x16x32_bf16 v[120:123], v[72:75], v[128:131], v[104:107]
	v_mfma_f32_16x16x32_bf16 v[72:75], v[72:75], v[154:157], v[76:79]
	v_mfma_f32_16x16x32_bf16 v[172:175], v[56:59], v[128:131], v[100:103]
	v_mfma_f32_16x16x32_bf16 v[56:59], v[56:59], v[154:157], v[60:63]
	v_add_u32_e32 v108, 0x80, v225
	v_add_u32_e32 v109, 0x1280, v225
	v_add_u32_e32 v110, 0xa0, v225
	v_add_u32_e32 v111, 0x12a0, v225
	v_add_u32_e32 v159, 0xc0, v225
	v_add_u32_e32 v160, 0x12c0, v225
	v_add_u32_e32 v176, 0xe0, v225
	v_add_u32_e32 v177, 0x12e0, v225
	ds_read_b64_tr_b16 v[104:105], v108
	ds_read_b64_tr_b16 v[106:107], v109
	ds_read_b64_tr_b16 v[100:101], v110
	ds_read_b64_tr_b16 v[102:103], v111
	ds_read_b64_tr_b16 v[76:77], v159
	ds_read_b64_tr_b16 v[78:79], v160
	ds_read_b64_tr_b16 v[60:61], v176
	ds_read_b64_tr_b16 v[62:63], v177
	s_waitcnt lgkmcnt(0)
	s_nop 0
	v_mfma_f32_16x16x32_bf16 v[88:91], v[100:103], v[128:131], v[88:91]
	v_mfma_f32_16x16x32_bf16 v[84:87], v[76:79], v[128:131], v[84:87]
	v_mfma_f32_16x16x32_bf16 v[52:55], v[76:79], v[154:157], v[52:55]
	v_mfma_f32_16x16x32_bf16 v[80:83], v[60:63], v[128:131], v[80:83]
	v_mfma_f32_16x16x32_bf16 v[48:51], v[60:63], v[154:157], v[48:51]
	v_mfma_f32_16x16x32_bf16 v[176:179], v[104:107], v[128:131], v[92:95]
	v_mfma_f32_16x16x32_bf16 v[180:183], v[104:107], v[154:157], v[32:35]
	v_mfma_f32_16x16x32_bf16 v[184:187], v[100:103], v[154:157], v[44:47]
	s_nop 0
	v_add_u32_e32 v92, 0x2400, v225
	v_add_u32_e32 v93, 0x3600, v225
	v_add_u32_e32 v94, 0x2420, v225
	v_add_u32_e32 v95, 0x3620, v225
	v_add_u32_e32 v100, 0x2440, v225
	v_add_u32_e32 v101, 0x3640, v225
	v_add_u32_e32 v102, 0x2460, v225
	v_add_u32_e32 v103, 0x3660, v225
	ds_read_b64_tr_b16 v[76:77], v92
	ds_read_b64_tr_b16 v[78:79], v93
	ds_read_b64_tr_b16 v[60:61], v94
	ds_read_b64_tr_b16 v[62:63], v95
	ds_read_b64_tr_b16 v[44:45], v100
	ds_read_b64_tr_b16 v[46:47], v101
	ds_read_b64_tr_b16 v[32:33], v102
	ds_read_b64_tr_b16 v[34:35], v103
	s_waitcnt lgkmcnt(0)
	v_mov_b32_e32 v131, v234
	v_mov_b32_e32 v130, v232
	v_mov_b32_e32 v129, v231
	v_mov_b32_e32 v128, v229
	v_mov_b32_e32 v157, v250
	v_mov_b32_e32 v156, v249
	v_mov_b32_e32 v155, v248
	v_mov_b32_e32 v154, v247
	v_mfma_f32_16x16x32_bf16 v[108:111], v[76:79], v[128:131], v[112:115]
	s_nop 0
	v_mfma_f32_16x16x32_bf16 v[76:79], v[76:79], v[154:157], v[116:119]
	v_mfma_f32_16x16x32_bf16 v[104:107], v[60:63], v[128:131], v[124:127]
	v_mfma_f32_16x16x32_bf16 v[60:63], v[60:63], v[154:157], v[96:99]
	v_mfma_f32_16x16x32_bf16 v[100:103], v[44:47], v[128:131], v[120:123]
	v_mfma_f32_16x16x32_bf16 v[44:47], v[44:47], v[154:157], v[72:75]
	v_mfma_f32_16x16x32_bf16 v[92:95], v[32:35], v[128:131], v[172:175]
	v_mfma_f32_16x16x32_bf16 v[32:35], v[32:35], v[154:157], v[56:59]
	v_add_u32_e32 v96, 0x2480, v225
	v_add_u32_e32 v97, 0x3680, v225
	v_add_u32_e32 v98, 0x24a0, v225
	v_add_u32_e32 v99, 0x36a0, v225
	v_add_u32_e32 v120, 0x24c0, v225
	v_add_u32_e32 v121, 0x36c0, v225
	v_add_u32_e32 v122, 0x24e0, v225
	v_add_u32_e32 v123, 0x36e0, v225
	ds_read_b64_tr_b16 v[72:73], v96
	ds_read_b64_tr_b16 v[74:75], v97
	ds_read_b64_tr_b16 v[56:57], v98
	ds_read_b64_tr_b16 v[58:59], v99
	ds_read_b64_tr_b16 v[116:117], v120
	ds_read_b64_tr_b16 v[118:119], v121
	ds_read_b64_tr_b16 v[112:113], v122
	ds_read_b64_tr_b16 v[114:115], v123
	s_waitcnt lgkmcnt(0)
	s_nop 0
	v_mfma_f32_16x16x32_bf16 v[96:99], v[72:75], v[128:131], v[176:179]
	v_mfma_f32_16x16x32_bf16 v[72:75], v[72:75], v[154:157], v[180:183]
	v_mfma_f32_16x16x32_bf16 v[88:91], v[56:59], v[128:131], v[88:91]
	v_mfma_f32_16x16x32_bf16 v[56:59], v[56:59], v[154:157], v[184:187]
	v_mfma_f32_16x16x32_bf16 v[84:87], v[116:119], v[128:131], v[84:87]
	v_mfma_f32_16x16x32_bf16 v[52:55], v[116:119], v[154:157], v[52:55]
	v_mfma_f32_16x16x32_bf16 v[80:83], v[112:115], v[128:131], v[80:83]
	v_mfma_f32_16x16x32_bf16 v[48:51], v[112:115], v[154:157], v[48:51]
	s_add_u32 s38, s38, 0x10000
	s_addc_u32 s39, s39, 0
	s_add_i32 s22, s22, 1
	v_add_u32_e32 v133, 64, v133
	v_add_u32_e32 v135, 64, v135
	v_add_u32_e32 v137, 64, v137
	v_add_u32_e32 v139, 64, v139
	s_cmp_lg_u32 s38, 0x180000
	v_mov_b32_e32 v154, v227
	v_mov_b32_e32 v112, v226
	s_cbranch_scc0 .LBB0_773
	s_branch .Lal1_head

	.amdhsa_kernel _Z11mega_kernel6Params
		.amdhsa_group_segment_fixed_size 0
		.amdhsa_private_segment_fixed_size 0
		.amdhsa_kernarg_size 496
		.amdhsa_user_sgpr_count 2
		.amdhsa_user_sgpr_dispatch_ptr 0
		.amdhsa_user_sgpr_queue_ptr 0
		.amdhsa_user_sgpr_kernarg_segment_ptr 1
		.amdhsa_user_sgpr_dispatch_id 0
		.amdhsa_user_sgpr_kernarg_preload_length 0
		.amdhsa_user_sgpr_kernarg_preload_offset 0
		.amdhsa_user_sgpr_private_segment_size 0
		.amdhsa_uses_dynamic_stack 0
		.amdhsa_enable_private_segment 0
		.amdhsa_system_sgpr_workgroup_id_x 1
		.amdhsa_system_sgpr_workgroup_id_y 0
		.amdhsa_system_sgpr_workgroup_id_z 0
		.amdhsa_system_sgpr_workgroup_info 0
		.amdhsa_system_vgpr_workitem_id 2
		.amdhsa_next_free_vgpr 256
		.amdhsa_next_free_sgpr 102
		.amdhsa_accum_offset 256
		.amdhsa_reserve_vcc 1
		.amdhsa_float_round_mode_32 0
		.amdhsa_float_round_mode_16_64 0
		.amdhsa_float_denorm_mode_32 3
		.amdhsa_float_denorm_mode_16_64 3
		.amdhsa_dx10_clamp 1
		.amdhsa_ieee_mode 1
		.amdhsa_fp16_overflow 0
		.amdhsa_tg_split 0
		.amdhsa_exception_fp_ieee_invalid_op 0
		.amdhsa_exception_fp_denorm_src 0
		.amdhsa_exception_fp_ieee_div_zero 0
		.amdhsa_exception_fp_ieee_overflow 0
		.amdhsa_exception_fp_ieee_underflow 0
		.amdhsa_exception_fp_ieee_inexact 0
		.amdhsa_exception_int_div_zero 0
	.end_amdhsa_kernel

amdhsa.kernels:
  - .agpr_count:     0
    .args:
      - .offset:         0
        .size:           240
        .value_kind:     by_value
      - .offset:         240
        .size:           4
        .value_kind:     hidden_block_count_x
      - .offset:         244
        .size:           4
        .value_kind:     hidden_block_count_y
      - .offset:         248
        .size:           4
        .value_kind:     hidden_block_count_z
      - .offset:         252
        .size:           2
        .value_kind:     hidden_group_size_x
      - .offset:         254
        .size:           2
        .value_kind:     hidden_group_size_y
      - .offset:         256
        .size:           2
        .value_kind:     hidden_group_size_z
      - .offset:         258
        .size:           2
        .value_kind:     hidden_remainder_x
      - .offset:         260
        .size:           2
        .value_kind:     hidden_remainder_y
      - .offset:         262
        .size:           2
        .value_kind:     hidden_remainder_z
      - .offset:         280
        .size:           8
        .value_kind:     hidden_global_offset_x
      - .offset:         288
        .size:           8
        .value_kind:     hidden_global_offset_y
      - .offset:         296
        .size:           8
        .value_kind:     hidden_global_offset_z
      - .offset:         304
        .size:           2
        .value_kind:     hidden_grid_dims
      - .offset:         328
        .size:           8
        .value_kind:     hidden_multigrid_sync_arg
      - .offset:         360
        .size:           4
        .value_kind:     hidden_dynamic_lds_size
    .group_segment_fixed_size: 0
    .kernarg_segment_align: 8
    .kernarg_segment_size: 496
    .language:       OpenCL C
    .language_version:
      - 2
      - 0
    .max_flat_workgroup_size: 512
    .name:           _Z11mega_kernel6Params
    .private_segment_fixed_size: 0
    .sgpr_count:     108
    .sgpr_spill_count: 212
    .symbol:         _Z11mega_kernel6Params.kd
    .uniform_work_group_size: 1
    .uses_dynamic_stack: false
    .vgpr_count:     256
    .vgpr_spill_count: 0
    .wavefront_size: 64
